# late-pass weight stores carry the nt hint (streaming lines leave L2 first)
# speedup vs baseline: 1.0120x; 1.0049x over previous
.Lgv2_common:
	s_lshr_b32 s13, s12, s11
	s_lshl_b32 s15, s13, s11
	s_sub_i32 s14, s12, s15
	s_add_i32 s15, s10, 6
	s_lshl_b32 s15, s13, s15
	s_lshl_b32 s21, s14, 7
	s_add_i32 s15, s15, s21
	s_lshl_b32 s29, 8, s10
	v_lshlrev_b32_e32 v4, s10, v2
	v_lshl_add_u32 v4, v3, 4, v4
	s_lshl_b32 s21, s13, 8
	s_waitcnt lgkmcnt(0)
	s_add_u32 s4, s4, s71
	s_addc_u32 s5, s5, 0
	s_add_u32 s4, s4, s15
	s_addc_u32 s5, s5, 0
	s_add_u32 s6, s6, s72
	s_addc_u32 s7, s7, 0
	s_add_u32 s6, s6, s21
	s_addc_u32 s7, s7, 0
	s_add_u32 s8, s8, s72
	s_addc_u32 s9, s9, 0
	s_add_u32 s8, s8, s21
	s_addc_u32 s9, s9, 0
	global_load_dwordx4 v[132:135], v4, s[4:5] nt
	s_add_u32 s4, s4, s29
	s_addc_u32 s5, s5, 0
	global_load_dwordx4 v[136:139], v4, s[4:5] nt
	s_add_u32 s4, s4, s29
	s_addc_u32 s5, s5, 0
	global_load_dwordx4 v[140:143], v4, s[4:5] nt
	s_add_u32 s4, s4, s29
	s_addc_u32 s5, s5, 0
	global_load_dwordx4 v[144:147], v4, s[4:5] nt
	s_add_u32 s4, s4, s29
	s_addc_u32 s5, s5, 0
	global_load_dwordx4 v[148:151], v4, s[4:5] nt
	s_add_u32 s4, s4, s29
	s_addc_u32 s5, s5, 0
	global_load_dwordx4 v[152:155], v4, s[4:5] nt
	s_add_u32 s4, s4, s29
	s_addc_u32 s5, s5, 0
	global_load_dwordx4 v[156:159], v4, s[4:5] nt
	s_add_u32 s4, s4, s29
	s_addc_u32 s5, s5, 0
	global_load_dwordx4 v[160:163], v4, s[4:5] nt
	global_load_dword v208, v5, s[6:7]
	global_load_dword v209, v5, s[8:9]
	s_lshl_b32 s15, s14, 17
	s_lshl_b32 s21, s13, 7
	s_add_i32 s15, s15, s21
	s_add_u32 s42, s16, s69
	s_addc_u32 s43, s17, 0
	s_add_u32 s42, s42, s15
	s_addc_u32 s43, s43, 0
	s_lshl_b32 s15, s14, 7
	s_add_u32 s44, s16, s70
	s_addc_u32 s45, s17, 0
	s_add_u32 s44, s44, s15
	s_addc_u32 s45, s45, 0
	s_addk_i32 s30, 0x800
	s_waitcnt vmcnt(10)
	ds_write_b32 v10, v206
	ds_write_b32 v10, v207 offset:256
	ds_read_b128 v[210:213], v11
	ds_read_b128 v[214:217], v11 offset:16
	ds_read_b128 v[218:221], v11 offset:256
	ds_read_b128 v[222:225], v11 offset:272
	s_waitcnt lgkmcnt(0)
	v_mul_f32_e32 v226, v100, v218
	v_mul_f32_e32 v100, v100, v210
	v_mul_f32_e32 v227, v101, v218
	v_mul_f32_e32 v101, v101, v210
	v_mul_f32_e32 v228, v102, v218
	v_mul_f32_e32 v102, v102, v210
	v_mul_f32_e32 v229, v103, v218
	v_mul_f32_e32 v103, v103, v210
	v_fmac_f32_e32 v226, v104, v219
	v_mul_f32_e32 v104, v104, v211
	v_fmac_f32_e32 v227, v105, v219
	v_mul_f32_e32 v105, v105, v211
	v_fmac_f32_e32 v228, v106, v219
	v_mul_f32_e32 v106, v106, v211
	v_fmac_f32_e32 v229, v107, v219
	v_mul_f32_e32 v107, v107, v211
	v_fmac_f32_e32 v226, v108, v220
	v_mul_f32_e32 v108, v108, v212
	v_fmac_f32_e32 v227, v109, v220
	v_mul_f32_e32 v109, v109, v212
	v_fmac_f32_e32 v228, v110, v220
	v_mul_f32_e32 v110, v110, v212
	v_fmac_f32_e32 v229, v111, v220
	v_mul_f32_e32 v111, v111, v212
	v_fmac_f32_e32 v226, v112, v221
	v_mul_f32_e32 v112, v112, v213
	v_fmac_f32_e32 v227, v113, v221
	v_mul_f32_e32 v113, v113, v213
	v_fmac_f32_e32 v228, v114, v221
	v_mul_f32_e32 v114, v114, v213
	v_fmac_f32_e32 v229, v115, v221
	v_mul_f32_e32 v115, v115, v213
	v_fmac_f32_e32 v226, v116, v222
	v_mul_f32_e32 v116, v116, v214
	v_fmac_f32_e32 v227, v117, v222
	v_mul_f32_e32 v117, v117, v214
	v_fmac_f32_e32 v228, v118, v222
	v_mul_f32_e32 v118, v118, v214
	v_fmac_f32_e32 v229, v119, v222
	v_mul_f32_e32 v119, v119, v214
	v_fmac_f32_e32 v226, v120, v223
	v_mul_f32_e32 v120, v120, v215
	v_fmac_f32_e32 v227, v121, v223
	v_mul_f32_e32 v121, v121, v215
	v_fmac_f32_e32 v228, v122, v223
	v_mul_f32_e32 v122, v122, v215
	v_fmac_f32_e32 v229, v123, v223
	v_mul_f32_e32 v123, v123, v215
	v_fmac_f32_e32 v226, v124, v224
	v_mul_f32_e32 v124, v124, v216
	v_fmac_f32_e32 v227, v125, v224
	v_mul_f32_e32 v125, v125, v216
	v_fmac_f32_e32 v228, v126, v224
	v_mul_f32_e32 v126, v126, v216
	v_fmac_f32_e32 v229, v127, v224
	v_mul_f32_e32 v127, v127, v216
	v_fmac_f32_e32 v226, v128, v225
	v_mul_f32_e32 v128, v128, v217
	v_fmac_f32_e32 v227, v129, v225
	v_mul_f32_e32 v129, v129, v217
	v_fmac_f32_e32 v228, v130, v225
	v_mul_f32_e32 v130, v130, v217
	v_fmac_f32_e32 v229, v131, v225
	v_mul_f32_e32 v131, v131, v217
	ds_write_b128 v21, v[100:103]
	ds_write_b128 v22, v[104:107] offset:1024
	ds_write_b128 v23, v[108:111] offset:2048
	ds_write_b128 v24, v[112:115] offset:3072
	ds_write_b128 v25, v[116:119] offset:4096
	ds_write_b128 v26, v[120:123] offset:5120
	ds_write_b128 v27, v[124:127] offset:6144
	ds_write_b128 v28, v[128:131] offset:7168
	ds_read2_b32 v[100:101], v29 offset1:32
	ds_read2_b32 v[102:103], v29 offset0:64 offset1:96
	ds_read2_b32 v[104:105], v29 offset0:128 offset1:160
	ds_read2_b32 v[106:107], v29 offset0:192 offset1:224
	ds_read2_b32 v[108:109], v30 offset1:32
	ds_read2_b32 v[110:111], v30 offset0:64 offset1:96
	ds_read2_b32 v[112:113], v30 offset0:128 offset1:160
	ds_read2_b32 v[114:115], v30 offset0:192 offset1:224
	ds_read2_b32 v[116:117], v31 offset1:32
	ds_read2_b32 v[118:119], v31 offset0:64 offset1:96
	ds_read2_b32 v[120:121], v31 offset0:128 offset1:160
	ds_read2_b32 v[122:123], v31 offset0:192 offset1:224
	ds_read2_b32 v[124:125], v32 offset1:32
	ds_read2_b32 v[126:127], v32 offset0:64 offset1:96
	ds_read2_b32 v[128:129], v32 offset0:128 offset1:160
	ds_read2_b32 v[130:131], v32 offset0:192 offset1:224
	ds_bpermute_b32 v234, v12, v226
	ds_bpermute_b32 v235, v12, v227
	ds_bpermute_b32 v236, v12, v228
	ds_bpermute_b32 v237, v12, v229
	s_waitcnt lgkmcnt(4)
	v_cvt_pk_bf16_f32 v164, v100, v101
	v_cvt_pk_bf16_f32 v165, v102, v103
	v_cvt_pk_bf16_f32 v166, v104, v105
	v_cvt_pk_bf16_f32 v167, v106, v107
	v_cvt_pk_bf16_f32 v168, v108, v109
	v_cvt_pk_bf16_f32 v169, v110, v111
	v_cvt_pk_bf16_f32 v170, v112, v113
	v_cvt_pk_bf16_f32 v171, v114, v115
	v_cvt_pk_bf16_f32 v172, v116, v117
	v_cvt_pk_bf16_f32 v173, v118, v119
	v_cvt_pk_bf16_f32 v174, v120, v121
	v_cvt_pk_bf16_f32 v175, v122, v123
	v_cvt_pk_bf16_f32 v176, v124, v125
	v_cvt_pk_bf16_f32 v177, v126, v127
	v_cvt_pk_bf16_f32 v178, v128, v129
	v_cvt_pk_bf16_f32 v179, v130, v131
	s_waitcnt lgkmcnt(0)
	v_add_f32_e32 v226, v226, v234
	v_add_f32_e32 v227, v227, v235
	v_add_f32_e32 v228, v228, v236
	v_add_f32_e32 v229, v229, v237
	ds_bpermute_b32 v234, v13, v226
	ds_bpermute_b32 v235, v13, v227
	ds_bpermute_b32 v236, v13, v228
	ds_bpermute_b32 v237, v13, v229
	v_lshlrev_b32_e32 v238, 16, v164
	v_and_b32_e32 v239, s59, v164
	v_add_f32_e32 v230, v238, v239
	v_lshlrev_b32_e32 v238, 16, v165
	v_and_b32_e32 v239, s59, v165
	v_add_f32_e32 v230, v230, v238
	v_add_f32_e32 v230, v230, v239
	v_lshlrev_b32_e32 v238, 16, v166
	v_and_b32_e32 v239, s59, v166
	v_add_f32_e32 v230, v230, v238
	v_add_f32_e32 v230, v230, v239
	v_lshlrev_b32_e32 v238, 16, v167
	v_and_b32_e32 v239, s59, v167
	v_add_f32_e32 v230, v230, v238
	v_add_f32_e32 v230, v230, v239
	v_lshlrev_b32_e32 v238, 16, v168
	v_and_b32_e32 v239, s59, v168
	v_add_f32_e32 v231, v238, v239
	v_lshlrev_b32_e32 v238, 16, v169
	v_and_b32_e32 v239, s59, v169
	v_add_f32_e32 v231, v231, v238
	v_add_f32_e32 v231, v231, v239
	v_lshlrev_b32_e32 v238, 16, v170
	v_and_b32_e32 v239, s59, v170
	v_add_f32_e32 v231, v231, v238
	v_add_f32_e32 v231, v231, v239
	v_lshlrev_b32_e32 v238, 16, v171
	v_and_b32_e32 v239, s59, v171
	v_add_f32_e32 v231, v231, v238
	v_add_f32_e32 v231, v231, v239
	s_waitcnt lgkmcnt(0)
	v_add_f32_e32 v226, v226, v234
	v_add_f32_e32 v227, v227, v235
	v_add_f32_e32 v228, v228, v236
	v_add_f32_e32 v229, v229, v237
	ds_bpermute_b32 v234, v14, v226
	ds_bpermute_b32 v235, v14, v227
	ds_bpermute_b32 v236, v14, v228
	ds_bpermute_b32 v237, v14, v229
	v_lshlrev_b32_e32 v238, 16, v172
	v_and_b32_e32 v239, s59, v172
	v_add_f32_e32 v232, v238, v239
	v_lshlrev_b32_e32 v238, 16, v173
	v_and_b32_e32 v239, s59, v173
	v_add_f32_e32 v232, v232, v238
	v_add_f32_e32 v232, v232, v239
	v_lshlrev_b32_e32 v238, 16, v174
	v_and_b32_e32 v239, s59, v174
	v_add_f32_e32 v232, v232, v238
	v_add_f32_e32 v232, v232, v239
	v_lshlrev_b32_e32 v238, 16, v175
	v_and_b32_e32 v239, s59, v175
	v_add_f32_e32 v232, v232, v238
	v_add_f32_e32 v232, v232, v239
	v_lshlrev_b32_e32 v238, 16, v176
	v_and_b32_e32 v239, s59, v176
	v_add_f32_e32 v233, v238, v239
	v_lshlrev_b32_e32 v238, 16, v177
	v_and_b32_e32 v239, s59, v177
	v_add_f32_e32 v233, v233, v238
	v_add_f32_e32 v233, v233, v239
	v_lshlrev_b32_e32 v238, 16, v178
	v_and_b32_e32 v239, s59, v178
	v_add_f32_e32 v233, v233, v238
	v_add_f32_e32 v233, v233, v239
	v_lshlrev_b32_e32 v238, 16, v179
	v_and_b32_e32 v239, s59, v179
	v_add_f32_e32 v233, v233, v238
	v_add_f32_e32 v233, v233, v239
	s_nop 1
	v_add_f32_dpp v230, v230, v230 quad_perm:[1,0,3,2] row_mask:0xf bank_mask:0xf
	v_add_f32_dpp v231, v231, v231 quad_perm:[1,0,3,2] row_mask:0xf bank_mask:0xf
	v_add_f32_dpp v232, v232, v232 quad_perm:[1,0,3,2] row_mask:0xf bank_mask:0xf
	v_add_f32_dpp v233, v233, v233 quad_perm:[1,0,3,2] row_mask:0xf bank_mask:0xf
	v_add_f32_dpp v230, v230, v230 quad_perm:[2,3,0,1] row_mask:0xf bank_mask:0xf
	v_add_f32_dpp v231, v231, v231 quad_perm:[2,3,0,1] row_mask:0xf bank_mask:0xf
	v_add_f32_dpp v232, v232, v232 quad_perm:[2,3,0,1] row_mask:0xf bank_mask:0xf
	v_add_f32_dpp v233, v233, v233 quad_perm:[2,3,0,1] row_mask:0xf bank_mask:0xf
	v_add_f32_dpp v230, v230, v230 row_half_mirror row_mask:0xf bank_mask:0xf
	v_add_f32_dpp v231, v231, v231 row_half_mirror row_mask:0xf bank_mask:0xf
	v_add_f32_dpp v232, v232, v232 row_half_mirror row_mask:0xf bank_mask:0xf
	v_add_f32_dpp v233, v233, v233 row_half_mirror row_mask:0xf bank_mask:0xf
	s_waitcnt lgkmcnt(0)
	v_add_f32_e32 v226, v226, v234
	v_add_f32_e32 v227, v227, v235
	v_add_f32_e32 v228, v228, v236
	v_add_f32_e32 v229, v229, v237
	global_store_dwordx4 v17, v[164:167], s[36:37] nt
	global_store_dwordx4 v18, v[168:171], s[36:37] nt
	global_store_dwordx4 v19, v[172:175], s[36:37] nt
	global_store_dwordx4 v20, v[176:179], s[36:37] nt
	s_add_u32 s48, s38, s40
	s_addc_u32 s49, s39, 0
	s_mov_b64 exec, s[56:57]
	global_atomic_add_f32 v15, v230, s[38:39]
	global_atomic_add_f32 v15, v231, s[38:39] offset:32
	global_atomic_add_f32 v15, v232, s[38:39] offset:64
	global_atomic_add_f32 v15, v233, s[38:39] offset:96
	s_mov_b64 exec, s[64:65]
	global_atomic_add_f32 v16, v226, s[48:49]
	global_atomic_add_f32 v16, v227, s[48:49] offset:4
	global_atomic_add_f32 v16, v228, s[48:49] offset:8
	global_atomic_add_f32 v16, v229, s[48:49] offset:12
	s_mov_b64 exec, -1
	s_cmp_lt_u32 s30, 0x4000
	s_cbranch_scc1 .Lgv3_w1
	s_cmp_lt_u32 s30, 0x5000
	s_cbranch_scc1 .Lgv3_pg
	s_cmp_lt_u32 s30, 0x5800
	s_cbranch_scc1 .Lgv3_wq
	s_cmp_lt_u32 s30, 0x5a00
	s_cbranch_scc1 .Lgv3_wk
	s_cmp_lt_u32 s30, 0x5c00
	s_cbranch_scc1 .Lgv3_wv
	s_mov_b32 s12, 0
	s_load_dwordx2 s[4:5], s[18:19], 0x98
	s_load_dwordx2 s[6:7], s[18:19], 0x100
	s_load_dwordx2 s[8:9], s[18:19], 0x108
	s_mov_b32 s10, 11
	s_mov_b32 s11, 4
	s_mov_b32 s69, 0x2d200000
	s_mov_b32 s70, 0x2e200000
	s_mov_b32 s40, 0x3000
	s_mov_b32 s71, 0
	s_mov_b32 s72, 0
	s_branch .Lgv3_common

.Lgv_loop:
	s_waitcnt vmcnt(22)
	ds_write_b32 v10, v208
	ds_write_b32 v10, v209 offset:256
	ds_read_b128 v[210:213], v11
	ds_read_b128 v[214:217], v11 offset:16
	ds_read_b128 v[218:221], v11 offset:256
	ds_read_b128 v[222:225], v11 offset:272
	s_waitcnt lgkmcnt(0)
	v_mul_f32_e32 v226, v132, v218
	v_mul_f32_e32 v132, v132, v210
	v_mul_f32_e32 v227, v133, v218
	v_mul_f32_e32 v133, v133, v210
	v_mul_f32_e32 v228, v134, v218
	v_mul_f32_e32 v134, v134, v210
	v_mul_f32_e32 v229, v135, v218
	v_mul_f32_e32 v135, v135, v210
	v_fmac_f32_e32 v226, v136, v219
	v_mul_f32_e32 v136, v136, v211
	v_fmac_f32_e32 v227, v137, v219
	v_mul_f32_e32 v137, v137, v211
	v_fmac_f32_e32 v228, v138, v219
	v_mul_f32_e32 v138, v138, v211
	v_fmac_f32_e32 v229, v139, v219
	v_mul_f32_e32 v139, v139, v211
	v_fmac_f32_e32 v226, v140, v220
	v_mul_f32_e32 v140, v140, v212
	v_fmac_f32_e32 v227, v141, v220
	v_mul_f32_e32 v141, v141, v212
	v_fmac_f32_e32 v228, v142, v220
	v_mul_f32_e32 v142, v142, v212
	v_fmac_f32_e32 v229, v143, v220
	v_mul_f32_e32 v143, v143, v212
	v_fmac_f32_e32 v226, v144, v221
	v_mul_f32_e32 v144, v144, v213
	v_fmac_f32_e32 v227, v145, v221
	v_mul_f32_e32 v145, v145, v213
	v_fmac_f32_e32 v228, v146, v221
	v_mul_f32_e32 v146, v146, v213
	v_fmac_f32_e32 v229, v147, v221
	v_mul_f32_e32 v147, v147, v213
	v_fmac_f32_e32 v226, v148, v222
	v_mul_f32_e32 v148, v148, v214
	v_fmac_f32_e32 v227, v149, v222
	v_mul_f32_e32 v149, v149, v214
	v_fmac_f32_e32 v228, v150, v222
	v_mul_f32_e32 v150, v150, v214
	v_fmac_f32_e32 v229, v151, v222
	v_mul_f32_e32 v151, v151, v214
	v_fmac_f32_e32 v226, v152, v223
	v_mul_f32_e32 v152, v152, v215
	v_fmac_f32_e32 v227, v153, v223
	v_mul_f32_e32 v153, v153, v215
	v_fmac_f32_e32 v228, v154, v223
	v_mul_f32_e32 v154, v154, v215
	v_fmac_f32_e32 v229, v155, v223
	v_mul_f32_e32 v155, v155, v215
	v_fmac_f32_e32 v226, v156, v224
	v_mul_f32_e32 v156, v156, v216
	v_fmac_f32_e32 v227, v157, v224
	v_mul_f32_e32 v157, v157, v216
	v_fmac_f32_e32 v228, v158, v224
	v_mul_f32_e32 v158, v158, v216
	v_fmac_f32_e32 v229, v159, v224
	v_mul_f32_e32 v159, v159, v216
	v_fmac_f32_e32 v226, v160, v225
	v_mul_f32_e32 v160, v160, v217
	v_fmac_f32_e32 v227, v161, v225
	v_mul_f32_e32 v161, v161, v217
	v_fmac_f32_e32 v228, v162, v225
	v_mul_f32_e32 v162, v162, v217
	v_fmac_f32_e32 v229, v163, v225
	v_mul_f32_e32 v163, v163, v217
	ds_write_b128 v21, v[132:135]
	ds_write_b128 v22, v[136:139] offset:1024
	ds_write_b128 v23, v[140:143] offset:2048
	ds_write_b128 v24, v[144:147] offset:3072
	ds_write_b128 v25, v[148:151] offset:4096
	ds_write_b128 v26, v[152:155] offset:5120
	ds_write_b128 v27, v[156:159] offset:6144
	ds_write_b128 v28, v[160:163] offset:7168
	ds_read2_b32 v[132:133], v29 offset1:32
	ds_read2_b32 v[134:135], v29 offset0:64 offset1:96
	ds_read2_b32 v[136:137], v29 offset0:128 offset1:160
	ds_read2_b32 v[138:139], v29 offset0:192 offset1:224
	ds_read2_b32 v[140:141], v30 offset1:32
	ds_read2_b32 v[142:143], v30 offset0:64 offset1:96
	ds_read2_b32 v[144:145], v30 offset0:128 offset1:160
	ds_read2_b32 v[146:147], v30 offset0:192 offset1:224
	ds_read2_b32 v[148:149], v31 offset1:32
	ds_read2_b32 v[150:151], v31 offset0:64 offset1:96
	ds_read2_b32 v[152:153], v31 offset0:128 offset1:160
	ds_read2_b32 v[154:155], v31 offset0:192 offset1:224
	ds_read2_b32 v[156:157], v32 offset1:32
	ds_read2_b32 v[158:159], v32 offset0:64 offset1:96
	ds_read2_b32 v[160:161], v32 offset0:128 offset1:160
	ds_read2_b32 v[162:163], v32 offset0:192 offset1:224
	ds_bpermute_b32 v234, v12, v226
	ds_bpermute_b32 v235, v12, v227
	ds_bpermute_b32 v236, v12, v228
	ds_bpermute_b32 v237, v12, v229
	s_waitcnt lgkmcnt(4)
	v_cvt_pk_bf16_f32 v190, v132, v133
	v_cvt_pk_bf16_f32 v191, v134, v135
	v_cvt_pk_bf16_f32 v192, v136, v137
	v_cvt_pk_bf16_f32 v193, v138, v139
	v_cvt_pk_bf16_f32 v194, v140, v141
	v_cvt_pk_bf16_f32 v195, v142, v143
	v_cvt_pk_bf16_f32 v196, v144, v145
	v_cvt_pk_bf16_f32 v197, v146, v147
	v_cvt_pk_bf16_f32 v198, v148, v149
	v_cvt_pk_bf16_f32 v199, v150, v151
	v_cvt_pk_bf16_f32 v200, v152, v153
	v_cvt_pk_bf16_f32 v201, v154, v155
	v_cvt_pk_bf16_f32 v202, v156, v157
	v_cvt_pk_bf16_f32 v203, v158, v159
	v_cvt_pk_bf16_f32 v204, v160, v161
	v_cvt_pk_bf16_f32 v205, v162, v163
	s_waitcnt lgkmcnt(0)
	v_add_f32_e32 v226, v226, v234
	v_add_f32_e32 v227, v227, v235
	v_add_f32_e32 v228, v228, v236
	v_add_f32_e32 v229, v229, v237
	ds_bpermute_b32 v234, v13, v226
	ds_bpermute_b32 v235, v13, v227
	ds_bpermute_b32 v236, v13, v228
	ds_bpermute_b32 v237, v13, v229
	v_lshlrev_b32_e32 v238, 16, v190
	v_and_b32_e32 v239, s59, v190
	v_add_f32_e32 v230, v238, v239
	v_lshlrev_b32_e32 v238, 16, v191
	v_and_b32_e32 v239, s59, v191
	v_add_f32_e32 v230, v230, v238
	v_add_f32_e32 v230, v230, v239
	v_lshlrev_b32_e32 v238, 16, v192
	v_and_b32_e32 v239, s59, v192
	v_add_f32_e32 v230, v230, v238
	v_add_f32_e32 v230, v230, v239
	v_lshlrev_b32_e32 v238, 16, v193
	v_and_b32_e32 v239, s59, v193
	v_add_f32_e32 v230, v230, v238
	v_add_f32_e32 v230, v230, v239
	v_lshlrev_b32_e32 v238, 16, v194
	v_and_b32_e32 v239, s59, v194
	v_add_f32_e32 v231, v238, v239
	v_lshlrev_b32_e32 v238, 16, v195
	v_and_b32_e32 v239, s59, v195
	v_add_f32_e32 v231, v231, v238
	v_add_f32_e32 v231, v231, v239
	v_lshlrev_b32_e32 v238, 16, v196
	v_and_b32_e32 v239, s59, v196
	v_add_f32_e32 v231, v231, v238
	v_add_f32_e32 v231, v231, v239
	v_lshlrev_b32_e32 v238, 16, v197
	v_and_b32_e32 v239, s59, v197
	v_add_f32_e32 v231, v231, v238
	v_add_f32_e32 v231, v231, v239
	s_waitcnt lgkmcnt(0)
	v_add_f32_e32 v226, v226, v234
	v_add_f32_e32 v227, v227, v235
	v_add_f32_e32 v228, v228, v236
	v_add_f32_e32 v229, v229, v237
	ds_bpermute_b32 v234, v14, v226
	ds_bpermute_b32 v235, v14, v227
	ds_bpermute_b32 v236, v14, v228
	ds_bpermute_b32 v237, v14, v229
	v_lshlrev_b32_e32 v238, 16, v198
	v_and_b32_e32 v239, s59, v198
	v_add_f32_e32 v232, v238, v239
	v_lshlrev_b32_e32 v238, 16, v199
	v_and_b32_e32 v239, s59, v199
	v_add_f32_e32 v232, v232, v238
	v_add_f32_e32 v232, v232, v239
	v_lshlrev_b32_e32 v238, 16, v200
	v_and_b32_e32 v239, s59, v200
	v_add_f32_e32 v232, v232, v238
	v_add_f32_e32 v232, v232, v239
	v_lshlrev_b32_e32 v238, 16, v201
	v_and_b32_e32 v239, s59, v201
	v_add_f32_e32 v232, v232, v238
	v_add_f32_e32 v232, v232, v239
	v_lshlrev_b32_e32 v238, 16, v202
	v_and_b32_e32 v239, s59, v202
	v_add_f32_e32 v233, v238, v239
	v_lshlrev_b32_e32 v238, 16, v203
	v_and_b32_e32 v239, s59, v203
	v_add_f32_e32 v233, v233, v238
	v_add_f32_e32 v233, v233, v239
	v_lshlrev_b32_e32 v238, 16, v204
	v_and_b32_e32 v239, s59, v204
	v_add_f32_e32 v233, v233, v238
	v_add_f32_e32 v233, v233, v239
	v_lshlrev_b32_e32 v238, 16, v205
	v_and_b32_e32 v239, s59, v205
	v_add_f32_e32 v233, v233, v238
	v_add_f32_e32 v233, v233, v239
	s_nop 1
	v_add_f32_dpp v230, v230, v230 quad_perm:[1,0,3,2] row_mask:0xf bank_mask:0xf
	v_add_f32_dpp v231, v231, v231 quad_perm:[1,0,3,2] row_mask:0xf bank_mask:0xf
	v_add_f32_dpp v232, v232, v232 quad_perm:[1,0,3,2] row_mask:0xf bank_mask:0xf
	v_add_f32_dpp v233, v233, v233 quad_perm:[1,0,3,2] row_mask:0xf bank_mask:0xf
	v_add_f32_dpp v230, v230, v230 quad_perm:[2,3,0,1] row_mask:0xf bank_mask:0xf
	v_add_f32_dpp v231, v231, v231 quad_perm:[2,3,0,1] row_mask:0xf bank_mask:0xf
	v_add_f32_dpp v232, v232, v232 quad_perm:[2,3,0,1] row_mask:0xf bank_mask:0xf
	v_add_f32_dpp v233, v233, v233 quad_perm:[2,3,0,1] row_mask:0xf bank_mask:0xf
	v_add_f32_dpp v230, v230, v230 row_half_mirror row_mask:0xf bank_mask:0xf
	v_add_f32_dpp v231, v231, v231 row_half_mirror row_mask:0xf bank_mask:0xf
	v_add_f32_dpp v232, v232, v232 row_half_mirror row_mask:0xf bank_mask:0xf
	v_add_f32_dpp v233, v233, v233 row_half_mirror row_mask:0xf bank_mask:0xf
	s_waitcnt lgkmcnt(0)
	v_add_f32_e32 v226, v226, v234
	v_add_f32_e32 v227, v227, v235
	v_add_f32_e32 v228, v228, v236
	v_add_f32_e32 v229, v229, v237
	global_store_dwordx4 v17, v[190:193], s[42:43] nt
	global_store_dwordx4 v18, v[194:197], s[42:43] nt
	global_store_dwordx4 v19, v[198:201], s[42:43] nt
	global_store_dwordx4 v20, v[202:205], s[42:43] nt
	s_add_u32 s48, s44, s47
	s_addc_u32 s49, s45, 0
	s_mov_b64 exec, s[56:57]
	global_atomic_add_f32 v15, v230, s[44:45]
	global_atomic_add_f32 v15, v231, s[44:45] offset:32
	global_atomic_add_f32 v15, v232, s[44:45] offset:64
	global_atomic_add_f32 v15, v233, s[44:45] offset:96
	s_mov_b64 exec, s[64:65]
	global_atomic_add_f32 v16, v226, s[48:49]
	global_atomic_add_f32 v16, v227, s[48:49] offset:4
	global_atomic_add_f32 v16, v228, s[48:49] offset:8
	global_atomic_add_f32 v16, v229, s[48:49] offset:12
	s_mov_b64 exec, -1
	s_cmp_lt_u32 s30, 0x4000
	s_cbranch_scc1 .Lgv4_w1
	s_cmp_lt_u32 s30, 0x5000
	s_cbranch_scc1 .Lgv4_pg
	s_cmp_lt_u32 s30, 0x5800
	s_cbranch_scc1 .Lgv4_wq
	s_cmp_lt_u32 s30, 0x5a00
	s_cbranch_scc1 .Lgv4_wk
	s_cmp_lt_u32 s30, 0x5c00
	s_cbranch_scc1 .Lgv4_wv
	s_mov_b32 s12, 0
	s_load_dwordx2 s[4:5], s[18:19], 0x98
	s_load_dwordx2 s[6:7], s[18:19], 0x100
	s_load_dwordx2 s[8:9], s[18:19], 0x108
	s_mov_b32 s10, 11
	s_mov_b32 s11, 4
	s_mov_b32 s69, 0x2d200000
	s_mov_b32 s70, 0x2e200000
	s_mov_b32 s47, 0x3000
	s_mov_b32 s71, 0
	s_mov_b32 s72, 0
	s_branch .Lgv4_common

.Lgv4_common:
	s_lshr_b32 s13, s12, s11
	s_lshl_b32 s15, s13, s11
	s_sub_i32 s14, s12, s15
	s_add_i32 s15, s10, 6
	s_lshl_b32 s15, s13, s15
	s_lshl_b32 s21, s14, 7
	s_add_i32 s15, s15, s21
	s_lshl_b32 s29, 8, s10
	v_lshlrev_b32_e32 v4, s10, v2
	v_lshl_add_u32 v4, v3, 4, v4
	s_lshl_b32 s21, s13, 8
	s_waitcnt lgkmcnt(0)
	s_add_u32 s4, s4, s71
	s_addc_u32 s5, s5, 0
	s_add_u32 s4, s4, s15
	s_addc_u32 s5, s5, 0
	s_add_u32 s6, s6, s72
	s_addc_u32 s7, s7, 0
	s_add_u32 s6, s6, s21
	s_addc_u32 s7, s7, 0
	s_add_u32 s8, s8, s72
	s_addc_u32 s9, s9, 0
	s_add_u32 s8, s8, s21
	s_addc_u32 s9, s9, 0
	global_load_dwordx4 v[132:135], v4, s[4:5] nt
	s_add_u32 s4, s4, s29
	s_addc_u32 s5, s5, 0
	global_load_dwordx4 v[136:139], v4, s[4:5] nt
	s_add_u32 s4, s4, s29
	s_addc_u32 s5, s5, 0
	global_load_dwordx4 v[140:143], v4, s[4:5] nt
	s_add_u32 s4, s4, s29
	s_addc_u32 s5, s5, 0
	global_load_dwordx4 v[144:147], v4, s[4:5] nt
	s_add_u32 s4, s4, s29
	s_addc_u32 s5, s5, 0
	global_load_dwordx4 v[148:151], v4, s[4:5] nt
	s_add_u32 s4, s4, s29
	s_addc_u32 s5, s5, 0
	global_load_dwordx4 v[152:155], v4, s[4:5] nt
	s_add_u32 s4, s4, s29
	s_addc_u32 s5, s5, 0
	global_load_dwordx4 v[156:159], v4, s[4:5] nt
	s_add_u32 s4, s4, s29
	s_addc_u32 s5, s5, 0
	global_load_dwordx4 v[160:163], v4, s[4:5] nt
	global_load_dword v208, v5, s[6:7]
	global_load_dword v209, v5, s[8:9]
	s_lshl_b32 s15, s14, 17
	s_lshl_b32 s21, s13, 7
	s_add_i32 s15, s15, s21
	s_add_u32 s42, s16, s69
	s_addc_u32 s43, s17, 0
	s_add_u32 s42, s42, s15
	s_addc_u32 s43, s43, 0
	s_lshl_b32 s15, s14, 7
	s_add_u32 s44, s16, s70
	s_addc_u32 s45, s17, 0
	s_add_u32 s44, s44, s15
	s_addc_u32 s45, s45, 0
	s_addk_i32 s30, 0x800
	s_waitcnt vmcnt(22)
	ds_write_b32 v10, v206
	ds_write_b32 v10, v207 offset:256
	ds_read_b128 v[210:213], v11
	ds_read_b128 v[214:217], v11 offset:16
	ds_read_b128 v[218:221], v11 offset:256
	ds_read_b128 v[222:225], v11 offset:272
	s_waitcnt lgkmcnt(0)
	v_mul_f32_e32 v226, v100, v218
	v_mul_f32_e32 v100, v100, v210
	v_mul_f32_e32 v227, v101, v218
	v_mul_f32_e32 v101, v101, v210
	v_mul_f32_e32 v228, v102, v218
	v_mul_f32_e32 v102, v102, v210
	v_mul_f32_e32 v229, v103, v218
	v_mul_f32_e32 v103, v103, v210
	v_fmac_f32_e32 v226, v104, v219
	v_mul_f32_e32 v104, v104, v211
	v_fmac_f32_e32 v227, v105, v219
	v_mul_f32_e32 v105, v105, v211
	v_fmac_f32_e32 v228, v106, v219
	v_mul_f32_e32 v106, v106, v211
	v_fmac_f32_e32 v229, v107, v219
	v_mul_f32_e32 v107, v107, v211
	v_fmac_f32_e32 v226, v108, v220
	v_mul_f32_e32 v108, v108, v212
	v_fmac_f32_e32 v227, v109, v220
	v_mul_f32_e32 v109, v109, v212
	v_fmac_f32_e32 v228, v110, v220
	v_mul_f32_e32 v110, v110, v212
	v_fmac_f32_e32 v229, v111, v220
	v_mul_f32_e32 v111, v111, v212
	v_fmac_f32_e32 v226, v112, v221
	v_mul_f32_e32 v112, v112, v213
	v_fmac_f32_e32 v227, v113, v221
	v_mul_f32_e32 v113, v113, v213
	v_fmac_f32_e32 v228, v114, v221
	v_mul_f32_e32 v114, v114, v213
	v_fmac_f32_e32 v229, v115, v221
	v_mul_f32_e32 v115, v115, v213
	v_fmac_f32_e32 v226, v116, v222
	v_mul_f32_e32 v116, v116, v214
	v_fmac_f32_e32 v227, v117, v222
	v_mul_f32_e32 v117, v117, v214
	v_fmac_f32_e32 v228, v118, v222
	v_mul_f32_e32 v118, v118, v214
	v_fmac_f32_e32 v229, v119, v222
	v_mul_f32_e32 v119, v119, v214
	v_fmac_f32_e32 v226, v120, v223
	v_mul_f32_e32 v120, v120, v215
	v_fmac_f32_e32 v227, v121, v223
	v_mul_f32_e32 v121, v121, v215
	v_fmac_f32_e32 v228, v122, v223
	v_mul_f32_e32 v122, v122, v215
	v_fmac_f32_e32 v229, v123, v223
	v_mul_f32_e32 v123, v123, v215
	v_fmac_f32_e32 v226, v124, v224
	v_mul_f32_e32 v124, v124, v216
	v_fmac_f32_e32 v227, v125, v224
	v_mul_f32_e32 v125, v125, v216
	v_fmac_f32_e32 v228, v126, v224
	v_mul_f32_e32 v126, v126, v216
	v_fmac_f32_e32 v229, v127, v224
	v_mul_f32_e32 v127, v127, v216
	v_fmac_f32_e32 v226, v128, v225
	v_mul_f32_e32 v128, v128, v217
	v_fmac_f32_e32 v227, v129, v225
	v_mul_f32_e32 v129, v129, v217
	v_fmac_f32_e32 v228, v130, v225
	v_mul_f32_e32 v130, v130, v217
	v_fmac_f32_e32 v229, v131, v225
	v_mul_f32_e32 v131, v131, v217
	ds_write_b128 v21, v[100:103]
	ds_write_b128 v22, v[104:107] offset:1024
	ds_write_b128 v23, v[108:111] offset:2048
	ds_write_b128 v24, v[112:115] offset:3072
	ds_write_b128 v25, v[116:119] offset:4096
	ds_write_b128 v26, v[120:123] offset:5120
	ds_write_b128 v27, v[124:127] offset:6144
	ds_write_b128 v28, v[128:131] offset:7168
	ds_read2_b32 v[100:101], v29 offset1:32
	ds_read2_b32 v[102:103], v29 offset0:64 offset1:96
	ds_read2_b32 v[104:105], v29 offset0:128 offset1:160
	ds_read2_b32 v[106:107], v29 offset0:192 offset1:224
	ds_read2_b32 v[108:109], v30 offset1:32
	ds_read2_b32 v[110:111], v30 offset0:64 offset1:96
	ds_read2_b32 v[112:113], v30 offset0:128 offset1:160
	ds_read2_b32 v[114:115], v30 offset0:192 offset1:224
	ds_read2_b32 v[116:117], v31 offset1:32
	ds_read2_b32 v[118:119], v31 offset0:64 offset1:96
	ds_read2_b32 v[120:121], v31 offset0:128 offset1:160
	ds_read2_b32 v[122:123], v31 offset0:192 offset1:224
	ds_read2_b32 v[124:125], v32 offset1:32
	ds_read2_b32 v[126:127], v32 offset0:64 offset1:96
	ds_read2_b32 v[128:129], v32 offset0:128 offset1:160
	ds_read2_b32 v[130:131], v32 offset0:192 offset1:224
	ds_bpermute_b32 v234, v12, v226
	ds_bpermute_b32 v235, v12, v227
	ds_bpermute_b32 v236, v12, v228
	ds_bpermute_b32 v237, v12, v229
	s_waitcnt lgkmcnt(4)
	v_cvt_pk_bf16_f32 v164, v100, v101
	v_cvt_pk_bf16_f32 v165, v102, v103
	v_cvt_pk_bf16_f32 v166, v104, v105
	v_cvt_pk_bf16_f32 v167, v106, v107
	v_cvt_pk_bf16_f32 v168, v108, v109
	v_cvt_pk_bf16_f32 v169, v110, v111
	v_cvt_pk_bf16_f32 v170, v112, v113
	v_cvt_pk_bf16_f32 v171, v114, v115
	v_cvt_pk_bf16_f32 v172, v116, v117
	v_cvt_pk_bf16_f32 v173, v118, v119
	v_cvt_pk_bf16_f32 v174, v120, v121
	v_cvt_pk_bf16_f32 v175, v122, v123
	v_cvt_pk_bf16_f32 v176, v124, v125
	v_cvt_pk_bf16_f32 v177, v126, v127
	v_cvt_pk_bf16_f32 v178, v128, v129
	v_cvt_pk_bf16_f32 v179, v130, v131
	s_waitcnt lgkmcnt(0)
	v_add_f32_e32 v226, v226, v234
	v_add_f32_e32 v227, v227, v235
	v_add_f32_e32 v228, v228, v236
	v_add_f32_e32 v229, v229, v237
	ds_bpermute_b32 v234, v13, v226
	ds_bpermute_b32 v235, v13, v227
	ds_bpermute_b32 v236, v13, v228
	ds_bpermute_b32 v237, v13, v229
	v_lshlrev_b32_e32 v238, 16, v164
	v_and_b32_e32 v239, s59, v164
	v_add_f32_e32 v230, v238, v239
	v_lshlrev_b32_e32 v238, 16, v165
	v_and_b32_e32 v239, s59, v165
	v_add_f32_e32 v230, v230, v238
	v_add_f32_e32 v230, v230, v239
	v_lshlrev_b32_e32 v238, 16, v166
	v_and_b32_e32 v239, s59, v166
	v_add_f32_e32 v230, v230, v238
	v_add_f32_e32 v230, v230, v239
	v_lshlrev_b32_e32 v238, 16, v167
	v_and_b32_e32 v239, s59, v167
	v_add_f32_e32 v230, v230, v238
	v_add_f32_e32 v230, v230, v239
	v_lshlrev_b32_e32 v238, 16, v168
	v_and_b32_e32 v239, s59, v168
	v_add_f32_e32 v231, v238, v239
	v_lshlrev_b32_e32 v238, 16, v169
	v_and_b32_e32 v239, s59, v169
	v_add_f32_e32 v231, v231, v238
	v_add_f32_e32 v231, v231, v239
	v_lshlrev_b32_e32 v238, 16, v170
	v_and_b32_e32 v239, s59, v170
	v_add_f32_e32 v231, v231, v238
	v_add_f32_e32 v231, v231, v239
	v_lshlrev_b32_e32 v238, 16, v171
	v_and_b32_e32 v239, s59, v171
	v_add_f32_e32 v231, v231, v238
	v_add_f32_e32 v231, v231, v239
	s_waitcnt lgkmcnt(0)
	v_add_f32_e32 v226, v226, v234
	v_add_f32_e32 v227, v227, v235
	v_add_f32_e32 v228, v228, v236
	v_add_f32_e32 v229, v229, v237
	ds_bpermute_b32 v234, v14, v226
	ds_bpermute_b32 v235, v14, v227
	ds_bpermute_b32 v236, v14, v228
	ds_bpermute_b32 v237, v14, v229
	v_lshlrev_b32_e32 v238, 16, v172
	v_and_b32_e32 v239, s59, v172
	v_add_f32_e32 v232, v238, v239
	v_lshlrev_b32_e32 v238, 16, v173
	v_and_b32_e32 v239, s59, v173
	v_add_f32_e32 v232, v232, v238
	v_add_f32_e32 v232, v232, v239
	v_lshlrev_b32_e32 v238, 16, v174
	v_and_b32_e32 v239, s59, v174
	v_add_f32_e32 v232, v232, v238
	v_add_f32_e32 v232, v232, v239
	v_lshlrev_b32_e32 v238, 16, v175
	v_and_b32_e32 v239, s59, v175
	v_add_f32_e32 v232, v232, v238
	v_add_f32_e32 v232, v232, v239
	v_lshlrev_b32_e32 v238, 16, v176
	v_and_b32_e32 v239, s59, v176
	v_add_f32_e32 v233, v238, v239
	v_lshlrev_b32_e32 v238, 16, v177
	v_and_b32_e32 v239, s59, v177
	v_add_f32_e32 v233, v233, v238
	v_add_f32_e32 v233, v233, v239
	v_lshlrev_b32_e32 v238, 16, v178
	v_and_b32_e32 v239, s59, v178
	v_add_f32_e32 v233, v233, v238
	v_add_f32_e32 v233, v233, v239
	v_lshlrev_b32_e32 v238, 16, v179
	v_and_b32_e32 v239, s59, v179
	v_add_f32_e32 v233, v233, v238
	v_add_f32_e32 v233, v233, v239
	s_nop 1
	v_add_f32_dpp v230, v230, v230 quad_perm:[1,0,3,2] row_mask:0xf bank_mask:0xf
	v_add_f32_dpp v231, v231, v231 quad_perm:[1,0,3,2] row_mask:0xf bank_mask:0xf
	v_add_f32_dpp v232, v232, v232 quad_perm:[1,0,3,2] row_mask:0xf bank_mask:0xf
	v_add_f32_dpp v233, v233, v233 quad_perm:[1,0,3,2] row_mask:0xf bank_mask:0xf
	v_add_f32_dpp v230, v230, v230 quad_perm:[2,3,0,1] row_mask:0xf bank_mask:0xf
	v_add_f32_dpp v231, v231, v231 quad_perm:[2,3,0,1] row_mask:0xf bank_mask:0xf
	v_add_f32_dpp v232, v232, v232 quad_perm:[2,3,0,1] row_mask:0xf bank_mask:0xf
	v_add_f32_dpp v233, v233, v233 quad_perm:[2,3,0,1] row_mask:0xf bank_mask:0xf
	v_add_f32_dpp v230, v230, v230 row_half_mirror row_mask:0xf bank_mask:0xf
	v_add_f32_dpp v231, v231, v231 row_half_mirror row_mask:0xf bank_mask:0xf
	v_add_f32_dpp v232, v232, v232 row_half_mirror row_mask:0xf bank_mask:0xf
	v_add_f32_dpp v233, v233, v233 row_half_mirror row_mask:0xf bank_mask:0xf
	s_waitcnt lgkmcnt(0)
	v_add_f32_e32 v226, v226, v234
	v_add_f32_e32 v227, v227, v235
	v_add_f32_e32 v228, v228, v236
	v_add_f32_e32 v229, v229, v237
	global_store_dwordx4 v17, v[164:167], s[36:37] nt
	global_store_dwordx4 v18, v[168:171], s[36:37] nt
	global_store_dwordx4 v19, v[172:175], s[36:37] nt
	global_store_dwordx4 v20, v[176:179], s[36:37] nt
	s_add_u32 s48, s38, s40
	s_addc_u32 s49, s39, 0
	s_mov_b64 exec, s[56:57]
	global_atomic_add_f32 v15, v230, s[38:39]
	global_atomic_add_f32 v15, v231, s[38:39] offset:32
	global_atomic_add_f32 v15, v232, s[38:39] offset:64
	global_atomic_add_f32 v15, v233, s[38:39] offset:96
	s_mov_b64 exec, s[64:65]
	global_atomic_add_f32 v16, v226, s[48:49]
	global_atomic_add_f32 v16, v227, s[48:49] offset:4
	global_atomic_add_f32 v16, v228, s[48:49] offset:8
	global_atomic_add_f32 v16, v229, s[48:49] offset:12
	s_mov_b64 exec, -1
	s_cmp_lt_u32 s30, 0x4000
	s_cbranch_scc1 .Lgv5_w1
	s_cmp_lt_u32 s30, 0x5000
	s_cbranch_scc1 .Lgv5_pg
	s_cmp_lt_u32 s30, 0x5800
	s_cbranch_scc1 .Lgv5_wq
	s_cmp_lt_u32 s30, 0x5a00
	s_cbranch_scc1 .Lgv5_wk
	s_cmp_lt_u32 s30, 0x5c00
	s_cbranch_scc1 .Lgv5_wv
	s_mov_b32 s12, 0
	s_load_dwordx2 s[4:5], s[18:19], 0x98
	s_load_dwordx2 s[6:7], s[18:19], 0x100
	s_load_dwordx2 s[8:9], s[18:19], 0x108
	s_mov_b32 s10, 11
	s_mov_b32 s11, 4
	s_mov_b32 s69, 0x2d200000
	s_mov_b32 s70, 0x2e200000
	s_mov_b32 s40, 0x3000
	s_mov_b32 s71, 0
	s_mov_b32 s72, 0
	s_branch .Lgv5_common

.Lgv5_common:
	s_lshr_b32 s13, s12, s11
	s_lshl_b32 s15, s13, s11
	s_sub_i32 s14, s12, s15
	s_add_i32 s15, s10, 6
	s_lshl_b32 s15, s13, s15
	s_lshl_b32 s21, s14, 7
	s_add_i32 s15, s15, s21
	s_lshl_b32 s29, 8, s10
	v_lshlrev_b32_e32 v4, s10, v2
	v_lshl_add_u32 v4, v3, 4, v4
	s_lshl_b32 s21, s13, 8
	s_waitcnt lgkmcnt(0)
	s_add_u32 s4, s4, s71
	s_addc_u32 s5, s5, 0
	s_add_u32 s4, s4, s15
	s_addc_u32 s5, s5, 0
	s_add_u32 s6, s6, s72
	s_addc_u32 s7, s7, 0
	s_add_u32 s6, s6, s21
	s_addc_u32 s7, s7, 0
	s_add_u32 s8, s8, s72
	s_addc_u32 s9, s9, 0
	s_add_u32 s8, s8, s21
	s_addc_u32 s9, s9, 0
	global_load_dwordx4 v[100:103], v4, s[4:5] nt
	s_add_u32 s4, s4, s29
	s_addc_u32 s5, s5, 0
	global_load_dwordx4 v[104:107], v4, s[4:5] nt
	s_add_u32 s4, s4, s29
	s_addc_u32 s5, s5, 0
	global_load_dwordx4 v[108:111], v4, s[4:5] nt
	s_add_u32 s4, s4, s29
	s_addc_u32 s5, s5, 0
	global_load_dwordx4 v[112:115], v4, s[4:5] nt
	s_add_u32 s4, s4, s29
	s_addc_u32 s5, s5, 0
	global_load_dwordx4 v[116:119], v4, s[4:5] nt
	s_add_u32 s4, s4, s29
	s_addc_u32 s5, s5, 0
	global_load_dwordx4 v[120:123], v4, s[4:5] nt
	s_add_u32 s4, s4, s29
	s_addc_u32 s5, s5, 0
	global_load_dwordx4 v[124:127], v4, s[4:5] nt
	s_add_u32 s4, s4, s29
	s_addc_u32 s5, s5, 0
	global_load_dwordx4 v[128:131], v4, s[4:5] nt
	global_load_dword v206, v5, s[6:7]
	global_load_dword v207, v5, s[8:9]
	s_lshl_b32 s15, s14, 17
	s_lshl_b32 s21, s13, 7
	s_add_i32 s15, s15, s21
	s_add_u32 s36, s16, s69
	s_addc_u32 s37, s17, 0
	s_add_u32 s36, s36, s15
	s_addc_u32 s37, s37, 0
	s_lshl_b32 s15, s14, 7
	s_add_u32 s38, s16, s70
	s_addc_u32 s39, s17, 0
	s_add_u32 s38, s38, s15
	s_addc_u32 s39, s39, 0
	s_addk_i32 s30, 0x800
	s_add_i32 s3, s3, -1
	s_cmp_lg_u32 s3, 0
	s_cbranch_scc1 .Lgv_loop
	s_waitcnt vmcnt(22)
	ds_write_b32 v10, v208
	ds_write_b32 v10, v209 offset:256
	ds_read_b128 v[210:213], v11
	ds_read_b128 v[214:217], v11 offset:16
	ds_read_b128 v[218:221], v11 offset:256
	ds_read_b128 v[222:225], v11 offset:272
	s_waitcnt lgkmcnt(0)
	v_mul_f32_e32 v226, v132, v218
	v_mul_f32_e32 v132, v132, v210
	v_mul_f32_e32 v227, v133, v218
	v_mul_f32_e32 v133, v133, v210
	v_mul_f32_e32 v228, v134, v218
	v_mul_f32_e32 v134, v134, v210
	v_mul_f32_e32 v229, v135, v218
	v_mul_f32_e32 v135, v135, v210
	v_fmac_f32_e32 v226, v136, v219
	v_mul_f32_e32 v136, v136, v211
	v_fmac_f32_e32 v227, v137, v219
	v_mul_f32_e32 v137, v137, v211
	v_fmac_f32_e32 v228, v138, v219
	v_mul_f32_e32 v138, v138, v211
	v_fmac_f32_e32 v229, v139, v219
	v_mul_f32_e32 v139, v139, v211
	v_fmac_f32_e32 v226, v140, v220
	v_mul_f32_e32 v140, v140, v212
	v_fmac_f32_e32 v227, v141, v220
	v_mul_f32_e32 v141, v141, v212
	v_fmac_f32_e32 v228, v142, v220
	v_mul_f32_e32 v142, v142, v212
	v_fmac_f32_e32 v229, v143, v220
	v_mul_f32_e32 v143, v143, v212
	v_fmac_f32_e32 v226, v144, v221
	v_mul_f32_e32 v144, v144, v213
	v_fmac_f32_e32 v227, v145, v221
	v_mul_f32_e32 v145, v145, v213
	v_fmac_f32_e32 v228, v146, v221
	v_mul_f32_e32 v146, v146, v213
	v_fmac_f32_e32 v229, v147, v221
	v_mul_f32_e32 v147, v147, v213
	v_fmac_f32_e32 v226, v148, v222
	v_mul_f32_e32 v148, v148, v214
	v_fmac_f32_e32 v227, v149, v222
	v_mul_f32_e32 v149, v149, v214
	v_fmac_f32_e32 v228, v150, v222
	v_mul_f32_e32 v150, v150, v214
	v_fmac_f32_e32 v229, v151, v222
	v_mul_f32_e32 v151, v151, v214
	v_fmac_f32_e32 v226, v152, v223
	v_mul_f32_e32 v152, v152, v215
	v_fmac_f32_e32 v227, v153, v223
	v_mul_f32_e32 v153, v153, v215
	v_fmac_f32_e32 v228, v154, v223
	v_mul_f32_e32 v154, v154, v215
	v_fmac_f32_e32 v229, v155, v223
	v_mul_f32_e32 v155, v155, v215
	v_fmac_f32_e32 v226, v156, v224
	v_mul_f32_e32 v156, v156, v216
	v_fmac_f32_e32 v227, v157, v224
	v_mul_f32_e32 v157, v157, v216
	v_fmac_f32_e32 v228, v158, v224
	v_mul_f32_e32 v158, v158, v216
	v_fmac_f32_e32 v229, v159, v224
	v_mul_f32_e32 v159, v159, v216
	v_fmac_f32_e32 v226, v160, v225
	v_mul_f32_e32 v160, v160, v217
	v_fmac_f32_e32 v227, v161, v225
	v_mul_f32_e32 v161, v161, v217
	v_fmac_f32_e32 v228, v162, v225
	v_mul_f32_e32 v162, v162, v217
	v_fmac_f32_e32 v229, v163, v225
	v_mul_f32_e32 v163, v163, v217
	ds_write_b128 v21, v[132:135]
	ds_write_b128 v22, v[136:139] offset:1024
	ds_write_b128 v23, v[140:143] offset:2048
	ds_write_b128 v24, v[144:147] offset:3072
	ds_write_b128 v25, v[148:151] offset:4096
	ds_write_b128 v26, v[152:155] offset:5120
	ds_write_b128 v27, v[156:159] offset:6144
	ds_write_b128 v28, v[160:163] offset:7168
	ds_read2_b32 v[132:133], v29 offset1:32
	ds_read2_b32 v[134:135], v29 offset0:64 offset1:96
	ds_read2_b32 v[136:137], v29 offset0:128 offset1:160
	ds_read2_b32 v[138:139], v29 offset0:192 offset1:224
	ds_read2_b32 v[140:141], v30 offset1:32
	ds_read2_b32 v[142:143], v30 offset0:64 offset1:96
	ds_read2_b32 v[144:145], v30 offset0:128 offset1:160
	ds_read2_b32 v[146:147], v30 offset0:192 offset1:224
	ds_read2_b32 v[148:149], v31 offset1:32
	ds_read2_b32 v[150:151], v31 offset0:64 offset1:96
	ds_read2_b32 v[152:153], v31 offset0:128 offset1:160
	ds_read2_b32 v[154:155], v31 offset0:192 offset1:224
	ds_read2_b32 v[156:157], v32 offset1:32
	ds_read2_b32 v[158:159], v32 offset0:64 offset1:96
	ds_read2_b32 v[160:161], v32 offset0:128 offset1:160
	ds_read2_b32 v[162:163], v32 offset0:192 offset1:224
	ds_bpermute_b32 v234, v12, v226
	ds_bpermute_b32 v235, v12, v227
	ds_bpermute_b32 v236, v12, v228
	ds_bpermute_b32 v237, v12, v229
	s_waitcnt lgkmcnt(4)
	v_cvt_pk_bf16_f32 v190, v132, v133
	v_cvt_pk_bf16_f32 v191, v134, v135
	v_cvt_pk_bf16_f32 v192, v136, v137
	v_cvt_pk_bf16_f32 v193, v138, v139
	v_cvt_pk_bf16_f32 v194, v140, v141
	v_cvt_pk_bf16_f32 v195, v142, v143
	v_cvt_pk_bf16_f32 v196, v144, v145
	v_cvt_pk_bf16_f32 v197, v146, v147
	v_cvt_pk_bf16_f32 v198, v148, v149
	v_cvt_pk_bf16_f32 v199, v150, v151
	v_cvt_pk_bf16_f32 v200, v152, v153
	v_cvt_pk_bf16_f32 v201, v154, v155
	v_cvt_pk_bf16_f32 v202, v156, v157
	v_cvt_pk_bf16_f32 v203, v158, v159
	v_cvt_pk_bf16_f32 v204, v160, v161
	v_cvt_pk_bf16_f32 v205, v162, v163
	s_waitcnt lgkmcnt(0)
	v_add_f32_e32 v226, v226, v234
	v_add_f32_e32 v227, v227, v235
	v_add_f32_e32 v228, v228, v236
	v_add_f32_e32 v229, v229, v237
	ds_bpermute_b32 v234, v13, v226
	ds_bpermute_b32 v235, v13, v227
	ds_bpermute_b32 v236, v13, v228
	ds_bpermute_b32 v237, v13, v229
	v_lshlrev_b32_e32 v238, 16, v190
	v_and_b32_e32 v239, s59, v190
	v_add_f32_e32 v230, v238, v239
	v_lshlrev_b32_e32 v238, 16, v191
	v_and_b32_e32 v239, s59, v191
	v_add_f32_e32 v230, v230, v238
	v_add_f32_e32 v230, v230, v239
	v_lshlrev_b32_e32 v238, 16, v192
	v_and_b32_e32 v239, s59, v192
	v_add_f32_e32 v230, v230, v238
	v_add_f32_e32 v230, v230, v239
	v_lshlrev_b32_e32 v238, 16, v193
	v_and_b32_e32 v239, s59, v193
	v_add_f32_e32 v230, v230, v238
	v_add_f32_e32 v230, v230, v239
	v_lshlrev_b32_e32 v238, 16, v194
	v_and_b32_e32 v239, s59, v194
	v_add_f32_e32 v231, v238, v239
	v_lshlrev_b32_e32 v238, 16, v195
	v_and_b32_e32 v239, s59, v195
	v_add_f32_e32 v231, v231, v238
	v_add_f32_e32 v231, v231, v239
	v_lshlrev_b32_e32 v238, 16, v196
	v_and_b32_e32 v239, s59, v196
	v_add_f32_e32 v231, v231, v238
	v_add_f32_e32 v231, v231, v239
	v_lshlrev_b32_e32 v238, 16, v197
	v_and_b32_e32 v239, s59, v197
	v_add_f32_e32 v231, v231, v238
	v_add_f32_e32 v231, v231, v239
	s_waitcnt lgkmcnt(0)
	v_add_f32_e32 v226, v226, v234
	v_add_f32_e32 v227, v227, v235
	v_add_f32_e32 v228, v228, v236
	v_add_f32_e32 v229, v229, v237
	ds_bpermute_b32 v234, v14, v226
	ds_bpermute_b32 v235, v14, v227
	ds_bpermute_b32 v236, v14, v228
	ds_bpermute_b32 v237, v14, v229
	v_lshlrev_b32_e32 v238, 16, v198
	v_and_b32_e32 v239, s59, v198
	v_add_f32_e32 v232, v238, v239
	v_lshlrev_b32_e32 v238, 16, v199
	v_and_b32_e32 v239, s59, v199
	v_add_f32_e32 v232, v232, v238
	v_add_f32_e32 v232, v232, v239
	v_lshlrev_b32_e32 v238, 16, v200
	v_and_b32_e32 v239, s59, v200
	v_add_f32_e32 v232, v232, v238
	v_add_f32_e32 v232, v232, v239
	v_lshlrev_b32_e32 v238, 16, v201
	v_and_b32_e32 v239, s59, v201
	v_add_f32_e32 v232, v232, v238
	v_add_f32_e32 v232, v232, v239
	v_lshlrev_b32_e32 v238, 16, v202
	v_and_b32_e32 v239, s59, v202
	v_add_f32_e32 v233, v238, v239
	v_lshlrev_b32_e32 v238, 16, v203
	v_and_b32_e32 v239, s59, v203
	v_add_f32_e32 v233, v233, v238
	v_add_f32_e32 v233, v233, v239
	v_lshlrev_b32_e32 v238, 16, v204
	v_and_b32_e32 v239, s59, v204
	v_add_f32_e32 v233, v233, v238
	v_add_f32_e32 v233, v233, v239
	v_lshlrev_b32_e32 v238, 16, v205
	v_and_b32_e32 v239, s59, v205
	v_add_f32_e32 v233, v233, v238
	v_add_f32_e32 v233, v233, v239
	s_nop 1
	v_add_f32_dpp v230, v230, v230 quad_perm:[1,0,3,2] row_mask:0xf bank_mask:0xf
	v_add_f32_dpp v231, v231, v231 quad_perm:[1,0,3,2] row_mask:0xf bank_mask:0xf
	v_add_f32_dpp v232, v232, v232 quad_perm:[1,0,3,2] row_mask:0xf bank_mask:0xf
	v_add_f32_dpp v233, v233, v233 quad_perm:[1,0,3,2] row_mask:0xf bank_mask:0xf
	v_add_f32_dpp v230, v230, v230 quad_perm:[2,3,0,1] row_mask:0xf bank_mask:0xf
	v_add_f32_dpp v231, v231, v231 quad_perm:[2,3,0,1] row_mask:0xf bank_mask:0xf
	v_add_f32_dpp v232, v232, v232 quad_perm:[2,3,0,1] row_mask:0xf bank_mask:0xf
	v_add_f32_dpp v233, v233, v233 quad_perm:[2,3,0,1] row_mask:0xf bank_mask:0xf
	v_add_f32_dpp v230, v230, v230 row_half_mirror row_mask:0xf bank_mask:0xf
	v_add_f32_dpp v231, v231, v231 row_half_mirror row_mask:0xf bank_mask:0xf
	v_add_f32_dpp v232, v232, v232 row_half_mirror row_mask:0xf bank_mask:0xf
	v_add_f32_dpp v233, v233, v233 row_half_mirror row_mask:0xf bank_mask:0xf
	s_waitcnt lgkmcnt(0)
	v_add_f32_e32 v226, v226, v234
	v_add_f32_e32 v227, v227, v235
	v_add_f32_e32 v228, v228, v236
	v_add_f32_e32 v229, v229, v237
	global_store_dwordx4 v17, v[190:193], s[42:43] nt
	global_store_dwordx4 v18, v[194:197], s[42:43] nt
	global_store_dwordx4 v19, v[198:201], s[42:43] nt
	global_store_dwordx4 v20, v[202:205], s[42:43] nt
	s_add_u32 s48, s44, s47
	s_addc_u32 s49, s45, 0
	s_mov_b64 exec, s[56:57]
	global_atomic_add_f32 v15, v230, s[44:45]
	global_atomic_add_f32 v15, v231, s[44:45] offset:32
	global_atomic_add_f32 v15, v232, s[44:45] offset:64
	global_atomic_add_f32 v15, v233, s[44:45] offset:96
	s_mov_b64 exec, s[64:65]
	global_atomic_add_f32 v16, v226, s[48:49]
	global_atomic_add_f32 v16, v227, s[48:49] offset:4
	global_atomic_add_f32 v16, v228, s[48:49] offset:8
	global_atomic_add_f32 v16, v229, s[48:49] offset:12
	s_mov_b64 exec, -1
	s_waitcnt vmcnt(0) lgkmcnt(0)
.Lgv_end:
.Lw2l_begin:
	s_cmp_eq_u32 s99, 1
	s_cbranch_scc1 .Lw2l_end
	v_readlane_b32 s43, v255, 8
	v_lshrrev_b32_e32 v2, 3, v244
	v_and_b32_e32 v3, 7, v244
	v_lshlrev_b32_e32 v4, 13, v2
	v_lshl_add_u32 v4, v3, 4, v4
	s_lshl_b32 s31, s85, 14
	v_lshlrev_b32_e32 v5, 7, v2
	v_add_u32_e32 v5, s31, v5
	v_xor_b32_e32 v6, 0, v3
	v_lshl_add_u32 v110, v6, 4, v5
	v_xor_b32_e32 v6, 1, v3
	v_lshl_add_u32 v111, v6, 4, v5
	v_xor_b32_e32 v6, 2, v3
	v_lshl_add_u32 v112, v6, 4, v5
	v_xor_b32_e32 v6, 3, v3
	v_lshl_add_u32 v113, v6, 4, v5
	v_xor_b32_e32 v6, 4, v3
	v_lshl_add_u32 v114, v6, 4, v5
	v_xor_b32_e32 v6, 5, v3
	v_lshl_add_u32 v115, v6, 4, v5
	v_xor_b32_e32 v6, 6, v3
	v_lshl_add_u32 v116, v6, 4, v5
	v_xor_b32_e32 v6, 7, v3
	v_lshl_add_u32 v117, v6, 4, v5
	v_lshlrev_b32_e32 v7, 10, v3
	v_add_u32_e32 v7, s31, v7
	v_add_u32_e32 v8, 0, v2
	v_lshrrev_b32_e32 v9, 2, v8
	v_xor_b32_e32 v9, v9, v3
	v_and_b32_e32 v8, 3, v8
	v_lshl_add_u32 v8, v9, 2, v8
	v_lshl_add_u32 v118, v8, 2, v7
	v_add_u32_e32 v8, 8, v2
	v_lshrrev_b32_e32 v9, 2, v8
	v_xor_b32_e32 v9, v9, v3
	v_and_b32_e32 v8, 3, v8
	v_lshl_add_u32 v8, v9, 2, v8
	v_lshl_add_u32 v119, v8, 2, v7
	v_add_u32_e32 v8, 16, v2
	v_lshrrev_b32_e32 v9, 2, v8
	v_xor_b32_e32 v9, v9, v3
	v_and_b32_e32 v8, 3, v8
	v_lshl_add_u32 v8, v9, 2, v8
	v_lshl_add_u32 v120, v8, 2, v7
	v_add_u32_e32 v8, 24, v2
	v_lshrrev_b32_e32 v9, 2, v8
	v_xor_b32_e32 v9, v9, v3
	v_and_b32_e32 v8, 3, v8
	v_lshl_add_u32 v8, v9, 2, v8
	v_lshl_add_u32 v121, v8, 2, v7
	s_load_dwordx2 s[26:27], s[86:87], 0xd8
	s_load_dwordx2 s[28:29], s[86:87], 0x118
	s_mov_b32 s30, s43
	v_lshlrev_b32_e32 v74, 14, v2
	v_lshl_add_u32 v74, v3, 4, v74
	v_add_u32_e32 v75, 0x20000, v74
	v_add_u32_e32 v76, 0x40000, v74
	v_add_u32_e32 v77, 0x60000, v74
	s_waitcnt lgkmcnt(0)
	s_add_u32 s28, s28, 0x3200000
	s_addc_u32 s29, s29, 0
	s_lshr_b32 s46, s30, 6
	s_and_b32 s47, s30, 63
	s_mov_b32 s40, s30
	s_lshl_b32 s36, s46, 19
	s_lshl_b32 s37, s47, 7
	s_add_i32 s36, s36, s37
	s_add_u32 s38, s26, s36
	s_addc_u32 s39, s27, 0
	global_load_dwordx4 v[10:13], v4, s[38:39] nt
	s_add_u32 s38, s38, 0x10000
	s_addc_u32 s39, s39, 0
	global_load_dwordx4 v[14:17], v4, s[38:39] nt
	s_add_u32 s38, s38, 0x10000
	s_addc_u32 s39, s39, 0
	global_load_dwordx4 v[18:21], v4, s[38:39] nt
	s_add_u32 s38, s38, 0x10000
	s_addc_u32 s39, s39, 0
	global_load_dwordx4 v[22:25], v4, s[38:39] nt
	s_add_u32 s38, s38, 0x10000
	s_addc_u32 s39, s39, 0
	global_load_dwordx4 v[26:29], v4, s[38:39] nt
	s_add_u32 s38, s38, 0x10000
	s_addc_u32 s39, s39, 0
	global_load_dwordx4 v[30:33], v4, s[38:39] nt
	s_add_u32 s38, s38, 0x10000
	s_addc_u32 s39, s39, 0
	global_load_dwordx4 v[34:37], v4, s[38:39] nt
	s_add_u32 s38, s38, 0x10000
	s_addc_u32 s39, s39, 0
	global_load_dwordx4 v[38:41], v4, s[38:39] nt
	s_addk_i32 s30, 0x800
	s_and_b32 s30, s30, 0x1fff
	s_lshr_b32 s46, s30, 6
	s_and_b32 s47, s30, 63
	s_mov_b32 s41, s30
	s_lshl_b32 s36, s46, 19
	s_lshl_b32 s37, s47, 7
	s_add_i32 s36, s36, s37
	s_add_u32 s38, s26, s36
	s_addc_u32 s39, s27, 0
	global_load_dwordx4 v[42:45], v4, s[38:39] nt
	s_add_u32 s38, s38, 0x10000
	s_addc_u32 s39, s39, 0
	global_load_dwordx4 v[46:49], v4, s[38:39] nt
	s_add_u32 s38, s38, 0x10000
	s_addc_u32 s39, s39, 0
	global_load_dwordx4 v[50:53], v4, s[38:39] nt
	s_add_u32 s38, s38, 0x10000
	s_addc_u32 s39, s39, 0
	global_load_dwordx4 v[54:57], v4, s[38:39] nt
	s_add_u32 s38, s38, 0x10000
	s_addc_u32 s39, s39, 0
	global_load_dwordx4 v[58:61], v4, s[38:39] nt
	s_add_u32 s38, s38, 0x10000
	s_addc_u32 s39, s39, 0
	global_load_dwordx4 v[62:65], v4, s[38:39] nt
	s_add_u32 s38, s38, 0x10000
	s_addc_u32 s39, s39, 0
	global_load_dwordx4 v[66:69], v4, s[38:39] nt
	s_add_u32 s38, s38, 0x10000
	s_addc_u32 s39, s39, 0
	global_load_dwordx4 v[70:73], v4, s[38:39] nt
	s_addk_i32 s30, 0x800
	s_and_b32 s30, s30, 0x1fff
	s_waitcnt vmcnt(8)
	ds_write_b128 v110, v[10:13]
	ds_write_b128 v111, v[14:17] offset:1024
	ds_write_b128 v112, v[18:21] offset:2048
	ds_write_b128 v113, v[22:25] offset:3072
	ds_write_b128 v114, v[26:29] offset:4096
	ds_write_b128 v115, v[30:33] offset:5120
	ds_write_b128 v116, v[34:37] offset:6144
	ds_write_b128 v117, v[38:41] offset:7168
	ds_read2_b32 v[10:11], v118 offset1:32
	ds_read2_b32 v[12:13], v118 offset0:64 offset1:96
	ds_read2_b32 v[14:15], v118 offset0:128 offset1:160
	ds_read2_b32 v[16:17], v118 offset0:192 offset1:224
	ds_read2_b32 v[18:19], v119 offset1:32
	ds_read2_b32 v[20:21], v119 offset0:64 offset1:96
	ds_read2_b32 v[22:23], v119 offset0:128 offset1:160
	ds_read2_b32 v[24:25], v119 offset0:192 offset1:224
	ds_read2_b32 v[26:27], v120 offset1:32
	ds_read2_b32 v[28:29], v120 offset0:64 offset1:96
	ds_read2_b32 v[30:31], v120 offset0:128 offset1:160
	ds_read2_b32 v[32:33], v120 offset0:192 offset1:224
	ds_read2_b32 v[34:35], v121 offset1:32
	ds_read2_b32 v[36:37], v121 offset0:64 offset1:96
	ds_read2_b32 v[38:39], v121 offset0:128 offset1:160
	ds_read2_b32 v[40:41], v121 offset0:192 offset1:224
	s_lshr_b32 s46, s40, 6
	s_and_b32 s47, s40, 63
	s_lshl_b32 s36, s47, 19
	s_lshl_b32 s37, s46, 7
	s_add_i32 s36, s36, s37
	s_add_u32 s38, s28, s36
	s_addc_u32 s39, s29, 0
	s_waitcnt lgkmcnt(12)
	v_cvt_pk_bf16_f32 v78, v10, v11
	v_cvt_pk_bf16_f32 v79, v12, v13
	v_cvt_pk_bf16_f32 v80, v14, v15
	v_cvt_pk_bf16_f32 v81, v16, v17
	s_waitcnt lgkmcnt(8)
	v_cvt_pk_bf16_f32 v82, v18, v19
	v_cvt_pk_bf16_f32 v83, v20, v21
	v_cvt_pk_bf16_f32 v84, v22, v23
	v_cvt_pk_bf16_f32 v85, v24, v25
	s_waitcnt lgkmcnt(4)
	v_cvt_pk_bf16_f32 v86, v26, v27
	v_cvt_pk_bf16_f32 v87, v28, v29
	v_cvt_pk_bf16_f32 v88, v30, v31
	v_cvt_pk_bf16_f32 v89, v32, v33
	s_waitcnt lgkmcnt(0)
	v_cvt_pk_bf16_f32 v90, v34, v35
	v_cvt_pk_bf16_f32 v91, v36, v37
	v_cvt_pk_bf16_f32 v92, v38, v39
	v_cvt_pk_bf16_f32 v93, v40, v41
	global_store_dwordx4 v74, v[78:81], s[38:39] nt
	global_store_dwordx4 v75, v[82:85], s[38:39] nt
	global_store_dwordx4 v76, v[86:89], s[38:39] nt
	global_store_dwordx4 v77, v[90:93], s[38:39] nt
	s_lshr_b32 s46, s30, 6
	s_and_b32 s47, s30, 63
	s_mov_b32 s40, s30
	s_lshl_b32 s36, s46, 19
	s_lshl_b32 s37, s47, 7
	s_add_i32 s36, s36, s37
	s_add_u32 s38, s26, s36
	s_addc_u32 s39, s27, 0
	global_load_dwordx4 v[10:13], v4, s[38:39] nt
	s_add_u32 s38, s38, 0x10000
	s_addc_u32 s39, s39, 0
	global_load_dwordx4 v[14:17], v4, s[38:39] nt
	s_add_u32 s38, s38, 0x10000
	s_addc_u32 s39, s39, 0
	global_load_dwordx4 v[18:21], v4, s[38:39] nt
	s_add_u32 s38, s38, 0x10000
	s_addc_u32 s39, s39, 0
	global_load_dwordx4 v[22:25], v4, s[38:39] nt
	s_add_u32 s38, s38, 0x10000
	s_addc_u32 s39, s39, 0
	global_load_dwordx4 v[26:29], v4, s[38:39] nt
	s_add_u32 s38, s38, 0x10000
	s_addc_u32 s39, s39, 0
	global_load_dwordx4 v[30:33], v4, s[38:39] nt
	s_add_u32 s38, s38, 0x10000
	s_addc_u32 s39, s39, 0
	global_load_dwordx4 v[34:37], v4, s[38:39] nt
	s_add_u32 s38, s38, 0x10000
	s_addc_u32 s39, s39, 0
	global_load_dwordx4 v[38:41], v4, s[38:39] nt
	s_addk_i32 s30, 0x800
	s_and_b32 s30, s30, 0x1fff
	s_waitcnt vmcnt(12)
	ds_write_b128 v110, v[42:45]
	ds_write_b128 v111, v[46:49] offset:1024
	ds_write_b128 v112, v[50:53] offset:2048
	ds_write_b128 v113, v[54:57] offset:3072
	ds_write_b128 v114, v[58:61] offset:4096
	ds_write_b128 v115, v[62:65] offset:5120
	ds_write_b128 v116, v[66:69] offset:6144
	ds_write_b128 v117, v[70:73] offset:7168
	ds_read2_b32 v[42:43], v118 offset1:32
	ds_read2_b32 v[44:45], v118 offset0:64 offset1:96
	ds_read2_b32 v[46:47], v118 offset0:128 offset1:160
	ds_read2_b32 v[48:49], v118 offset0:192 offset1:224
	ds_read2_b32 v[50:51], v119 offset1:32
	ds_read2_b32 v[52:53], v119 offset0:64 offset1:96
	ds_read2_b32 v[54:55], v119 offset0:128 offset1:160
	ds_read2_b32 v[56:57], v119 offset0:192 offset1:224
	ds_read2_b32 v[58:59], v120 offset1:32
	ds_read2_b32 v[60:61], v120 offset0:64 offset1:96
	ds_read2_b32 v[62:63], v120 offset0:128 offset1:160
	ds_read2_b32 v[64:65], v120 offset0:192 offset1:224
	ds_read2_b32 v[66:67], v121 offset1:32
	ds_read2_b32 v[68:69], v121 offset0:64 offset1:96
	ds_read2_b32 v[70:71], v121 offset0:128 offset1:160
	ds_read2_b32 v[72:73], v121 offset0:192 offset1:224
	s_lshr_b32 s46, s41, 6
	s_and_b32 s47, s41, 63
	s_lshl_b32 s36, s47, 19
	s_lshl_b32 s37, s46, 7
	s_add_i32 s36, s36, s37
	s_add_u32 s38, s28, s36
	s_addc_u32 s39, s29, 0
	s_waitcnt lgkmcnt(12)
	v_cvt_pk_bf16_f32 v94, v42, v43
	v_cvt_pk_bf16_f32 v95, v44, v45
	v_cvt_pk_bf16_f32 v96, v46, v47
	v_cvt_pk_bf16_f32 v97, v48, v49
	s_waitcnt lgkmcnt(8)
	v_cvt_pk_bf16_f32 v98, v50, v51
	v_cvt_pk_bf16_f32 v99, v52, v53
	v_cvt_pk_bf16_f32 v100, v54, v55
	v_cvt_pk_bf16_f32 v101, v56, v57
	s_waitcnt lgkmcnt(4)
	v_cvt_pk_bf16_f32 v102, v58, v59
	v_cvt_pk_bf16_f32 v103, v60, v61
	v_cvt_pk_bf16_f32 v104, v62, v63
	v_cvt_pk_bf16_f32 v105, v64, v65
	s_waitcnt lgkmcnt(0)
	v_cvt_pk_bf16_f32 v106, v66, v67
	v_cvt_pk_bf16_f32 v107, v68, v69
	v_cvt_pk_bf16_f32 v108, v70, v71
	v_cvt_pk_bf16_f32 v109, v72, v73
	global_store_dwordx4 v74, v[94:97], s[38:39] nt
	global_store_dwordx4 v75, v[98:101], s[38:39] nt
	global_store_dwordx4 v76, v[102:105], s[38:39] nt
	global_store_dwordx4 v77, v[106:109], s[38:39] nt
	s_lshr_b32 s46, s30, 6
	s_and_b32 s47, s30, 63
	s_mov_b32 s41, s30
	s_lshl_b32 s36, s46, 19
	s_lshl_b32 s37, s47, 7
	s_add_i32 s36, s36, s37
	s_add_u32 s38, s26, s36
	s_addc_u32 s39, s27, 0
	global_load_dwordx4 v[42:45], v4, s[38:39] nt
	s_add_u32 s38, s38, 0x10000
	s_addc_u32 s39, s39, 0
	global_load_dwordx4 v[46:49], v4, s[38:39] nt
	s_add_u32 s38, s38, 0x10000
	s_addc_u32 s39, s39, 0
	global_load_dwordx4 v[50:53], v4, s[38:39] nt
	s_add_u32 s38, s38, 0x10000
	s_addc_u32 s39, s39, 0
	global_load_dwordx4 v[54:57], v4, s[38:39] nt
	s_add_u32 s38, s38, 0x10000
	s_addc_u32 s39, s39, 0
	global_load_dwordx4 v[58:61], v4, s[38:39] nt
	s_add_u32 s38, s38, 0x10000
	s_addc_u32 s39, s39, 0
	global_load_dwordx4 v[62:65], v4, s[38:39] nt
	s_add_u32 s38, s38, 0x10000
	s_addc_u32 s39, s39, 0
	global_load_dwordx4 v[66:69], v4, s[38:39] nt
	s_add_u32 s38, s38, 0x10000
	s_addc_u32 s39, s39, 0
	global_load_dwordx4 v[70:73], v4, s[38:39] nt
	s_addk_i32 s30, 0x800
	s_and_b32 s30, s30, 0x1fff
	s_waitcnt vmcnt(12)
	ds_write_b128 v110, v[10:13]
	ds_write_b128 v111, v[14:17] offset:1024
	ds_write_b128 v112, v[18:21] offset:2048
	ds_write_b128 v113, v[22:25] offset:3072
	ds_write_b128 v114, v[26:29] offset:4096
	ds_write_b128 v115, v[30:33] offset:5120
	ds_write_b128 v116, v[34:37] offset:6144
	ds_write_b128 v117, v[38:41] offset:7168
	ds_read2_b32 v[10:11], v118 offset1:32
	ds_read2_b32 v[12:13], v118 offset0:64 offset1:96
	ds_read2_b32 v[14:15], v118 offset0:128 offset1:160
	ds_read2_b32 v[16:17], v118 offset0:192 offset1:224
	ds_read2_b32 v[18:19], v119 offset1:32
	ds_read2_b32 v[20:21], v119 offset0:64 offset1:96
	ds_read2_b32 v[22:23], v119 offset0:128 offset1:160
	ds_read2_b32 v[24:25], v119 offset0:192 offset1:224
	ds_read2_b32 v[26:27], v120 offset1:32
	ds_read2_b32 v[28:29], v120 offset0:64 offset1:96
	ds_read2_b32 v[30:31], v120 offset0:128 offset1:160
	ds_read2_b32 v[32:33], v120 offset0:192 offset1:224
	ds_read2_b32 v[34:35], v121 offset1:32
	ds_read2_b32 v[36:37], v121 offset0:64 offset1:96
	ds_read2_b32 v[38:39], v121 offset0:128 offset1:160
	ds_read2_b32 v[40:41], v121 offset0:192 offset1:224
	s_lshr_b32 s46, s40, 6
	s_and_b32 s47, s40, 63
	s_lshl_b32 s36, s47, 19
	s_lshl_b32 s37, s46, 7
	s_add_i32 s36, s36, s37
	s_add_u32 s38, s28, s36
	s_addc_u32 s39, s29, 0
	s_waitcnt lgkmcnt(12)
	v_cvt_pk_bf16_f32 v78, v10, v11
	v_cvt_pk_bf16_f32 v79, v12, v13
	v_cvt_pk_bf16_f32 v80, v14, v15
	v_cvt_pk_bf16_f32 v81, v16, v17
	s_waitcnt lgkmcnt(8)
	v_cvt_pk_bf16_f32 v82, v18, v19
	v_cvt_pk_bf16_f32 v83, v20, v21
	v_cvt_pk_bf16_f32 v84, v22, v23
	v_cvt_pk_bf16_f32 v85, v24, v25
	s_waitcnt lgkmcnt(4)
	v_cvt_pk_bf16_f32 v86, v26, v27
	v_cvt_pk_bf16_f32 v87, v28, v29
	v_cvt_pk_bf16_f32 v88, v30, v31
	v_cvt_pk_bf16_f32 v89, v32, v33
	s_waitcnt lgkmcnt(0)
	v_cvt_pk_bf16_f32 v90, v34, v35
	v_cvt_pk_bf16_f32 v91, v36, v37
	v_cvt_pk_bf16_f32 v92, v38, v39
	v_cvt_pk_bf16_f32 v93, v40, v41
	global_store_dwordx4 v74, v[78:81], s[38:39] nt
	global_store_dwordx4 v75, v[82:85], s[38:39] nt
	global_store_dwordx4 v76, v[86:89], s[38:39] nt
	global_store_dwordx4 v77, v[90:93], s[38:39] nt
	s_waitcnt vmcnt(4)
	ds_write_b128 v110, v[42:45]
	ds_write_b128 v111, v[46:49] offset:1024
	ds_write_b128 v112, v[50:53] offset:2048
	ds_write_b128 v113, v[54:57] offset:3072
	ds_write_b128 v114, v[58:61] offset:4096
	ds_write_b128 v115, v[62:65] offset:5120
	ds_write_b128 v116, v[66:69] offset:6144
	ds_write_b128 v117, v[70:73] offset:7168
	ds_read2_b32 v[42:43], v118 offset1:32
	ds_read2_b32 v[44:45], v118 offset0:64 offset1:96
	ds_read2_b32 v[46:47], v118 offset0:128 offset1:160
	ds_read2_b32 v[48:49], v118 offset0:192 offset1:224
	ds_read2_b32 v[50:51], v119 offset1:32
	ds_read2_b32 v[52:53], v119 offset0:64 offset1:96
	ds_read2_b32 v[54:55], v119 offset0:128 offset1:160
	ds_read2_b32 v[56:57], v119 offset0:192 offset1:224
	ds_read2_b32 v[58:59], v120 offset1:32
	ds_read2_b32 v[60:61], v120 offset0:64 offset1:96
	ds_read2_b32 v[62:63], v120 offset0:128 offset1:160
	ds_read2_b32 v[64:65], v120 offset0:192 offset1:224
	ds_read2_b32 v[66:67], v121 offset1:32
	ds_read2_b32 v[68:69], v121 offset0:64 offset1:96
	ds_read2_b32 v[70:71], v121 offset0:128 offset1:160
	ds_read2_b32 v[72:73], v121 offset0:192 offset1:224
	s_lshr_b32 s46, s41, 6
	s_and_b32 s47, s41, 63
	s_lshl_b32 s36, s47, 19
	s_lshl_b32 s37, s46, 7
	s_add_i32 s36, s36, s37
	s_add_u32 s38, s28, s36
	s_addc_u32 s39, s29, 0
	s_waitcnt lgkmcnt(12)
	v_cvt_pk_bf16_f32 v94, v42, v43
	v_cvt_pk_bf16_f32 v95, v44, v45
	v_cvt_pk_bf16_f32 v96, v46, v47
	v_cvt_pk_bf16_f32 v97, v48, v49
	s_waitcnt lgkmcnt(8)
	v_cvt_pk_bf16_f32 v98, v50, v51
	v_cvt_pk_bf16_f32 v99, v52, v53
	v_cvt_pk_bf16_f32 v100, v54, v55
	v_cvt_pk_bf16_f32 v101, v56, v57
	s_waitcnt lgkmcnt(4)
	v_cvt_pk_bf16_f32 v102, v58, v59
	v_cvt_pk_bf16_f32 v103, v60, v61
	v_cvt_pk_bf16_f32 v104, v62, v63
	v_cvt_pk_bf16_f32 v105, v64, v65
	s_waitcnt lgkmcnt(0)
	v_cvt_pk_bf16_f32 v106, v66, v67
	v_cvt_pk_bf16_f32 v107, v68, v69
	v_cvt_pk_bf16_f32 v108, v70, v71
	v_cvt_pk_bf16_f32 v109, v72, v73
	global_store_dwordx4 v74, v[94:97], s[38:39] nt
	global_store_dwordx4 v75, v[98:101], s[38:39] nt
	global_store_dwordx4 v76, v[102:105], s[38:39] nt
	global_store_dwordx4 v77, v[106:109], s[38:39] nt
	s_waitcnt vmcnt(0) lgkmcnt(0)
